# v27 with 2 wait states between v_add_co and v_addc_co in the hand-written address code (hazard hygiene); otherwise identical
# speedup vs baseline: 1.0011x; 1.0011x over previous
; __device__ __forceinline__ void phase_a1(const P& p, const Ctx& c, int seg) {
;     ...
;             u32x2 nraw = *(const u32x2*)(P0 + (unsigned)(row0 * ML_W + n * 4));
; #pragma unroll 1
;             for (int tt = 0; tt < 8; ++tt) {
;                 const unsigned row = (unsigned)(row0 + tt);
;                 const u32x2 raw = nraw;
;                 if (tt + 1 < 8) nraw = *(const u32x2*)(P0 + (unsigned)((row + 1) * ML_W + n * 4));
.LBB0_271:
	v_lshl_add_u32 v4, s46, 15, v2
	s_waitcnt lgkmcnt(0)
	v_lshl_add_u64 v[98:99], v[4:5], 1, s[10:11]
	global_load_dwordx2 v[116:117], v[98:99], off
	v_lshlrev_b32_e32 v208, 2, v170
	v_ashrrev_i32_e32 v209, 31, v208
	v_lshlrev_b64 v[208:209], 2, v[208:209]
	v_lshl_add_u64 v[210:211], s[22:23], 0, v[208:209]
	global_load_dwordx4 v[218:221], v[210:211], off
	v_lshl_add_u64 v[210:211], s[20:21], 0, v[208:209]
	global_load_dwordx4 v[222:225], v[210:211], off
	v_lshl_add_u64 v[210:211], s[54:55], 0, v[208:209]
	global_load_dwordx4 v[226:229], v[210:211], off
	v_lshl_add_u64 v[210:211], s[56:57], 0, v[208:209]
	global_load_dwordx4 v[230:233], v[210:211], off
	v_lshl_add_u64 v[210:211], s[68:69], 0, v[208:209]
	global_load_dwordx4 v[234:237], v[210:211], off
	v_add_co_u32_e32 v210, vcc, 0x2000, v98
	s_nop 1
	v_addc_co_u32_e32 v211, vcc, 0, v99, vcc
	global_load_dwordx2 v[238:239], v[210:211], off
	v_add_co_u32_e32 v210, vcc, 0x2000, v210
	s_nop 1
	v_addc_co_u32_e32 v211, vcc, 0, v211, vcc
	global_load_dwordx2 v[240:241], v[210:211], off
	v_add_co_u32_e32 v210, vcc, 0x2000, v210
	s_nop 1
	v_addc_co_u32_e32 v211, vcc, 0, v211, vcc
	global_load_dwordx2 v[242:243], v[210:211], off
	v_add_co_u32_e32 v210, vcc, 0x2000, v210
	s_nop 1
	v_addc_co_u32_e32 v211, vcc, 0, v211, vcc
	global_load_dwordx2 v[244:245], v[210:211], off
	v_add_co_u32_e32 v210, vcc, 0x2000, v210
	s_nop 1
	v_addc_co_u32_e32 v211, vcc, 0, v211, vcc
	global_load_dwordx2 v[246:247], v[210:211], off
	v_add_co_u32_e32 v210, vcc, 0x2000, v210
	s_nop 1
	v_addc_co_u32_e32 v211, vcc, 0, v211, vcc
	global_load_dwordx2 v[248:249], v[210:211], off
	v_add_co_u32_e32 v210, vcc, 0x2000, v210
	s_nop 1
	v_addc_co_u32_e32 v211, vcc, 0, v211, vcc
	global_load_dwordx2 v[250:251], v[210:211], off
	s_waitcnt vmcnt(13)
	v_lshlrev_b32_e32 v100, 16, v102
	v_and_b32_e32 v101, 0xffff0000, v102
	v_lshlrev_b32_e32 v99, 16, v103
	v_and_b32_e32 v137, 0xffff0000, v103
	v_lshlrev_b32_e32 v102, 16, v104
	v_and_b32_e32 v103, 0xffff0000, v104
	v_lshlrev_b32_e32 v104, 16, v105
	v_and_b32_e32 v138, 0xffff0000, v105
	v_lshlrev_b32_e32 v118, 16, v106
	v_and_b32_e32 v119, 0xffff0000, v106
	v_lshlrev_b32_e32 v98, 16, v107
	v_and_b32_e32 v120, 0xffff0000, v107
	s_mov_b32 s8, -16
	v_mov_b32_e32 v4, v136
	v_mov_b32_e32 v106, v135
	v_mov_b32_e32 v139, v3
	s_waitcnt vmcnt(0)
	v_mov_b64_e32 v[108:109], v[116:117]
	s_branch .LBB0_273

; __device__ __forceinline__ float bf2f(bf16_t b) { return __uint_as_float(((unsigned)b) << 16); }
; __device__ __forceinline__ void phase_b1(const P& p, const Ctx& c, int seg) {
;     ...
;         for (int e = c.tid; e < 16 * 288; e += 512) { const int row = e / 288, cc = e % 288, col = 4608 + cc;
;             const float cur = bf2f(P1[(size_t)(r0 + row) * P1W + col]);
;             float prev = 0.f; if (tl0 + row > 0) prev = bf2f(P1[(size_t)(r0 + row - 1) * P1W + col]); else if (seg > 0) prev = bf2f(PTr[(size_t)b * RW_SHIFT + col]);
;             const float pv = cur + p.rw_mu[col] * (prev - cur);
.LBB0_715:
	s_lshl_b32 s35, s34, 4
	s_ashr_i32 s8, s34, 5
	s_and_b32 s9, s35, 0x1f0
	s_mul_hi_i32 s10, s8, 0x2640
	s_mul_i32 s11, s8, 0x2640
	s_barrier
	s_mov_b64 s[12:13], exec
	v_readlane_b32 s14, v255, 46
	v_readlane_b32 s15, v255, 47
	s_and_b64 s[14:15], s[12:13], s[14:15]
	s_mov_b64 exec, s[14:15]
	s_cbranch_execz .LBB0_728
	v_readlane_b32 s14, v255, 43
	s_add_u32 s14, s14, s11
	v_readlane_b32 s15, v255, 45
	s_addc_u32 s15, s15, s10
	s_mov_b32 s39, 0x38e38e39
	s_movk_i32 s40, 0x2800
	v_mov_b32_e32 v80, v138
	v_mul_hi_i32 v2, v80, s39
	v_lshrrev_b32_e32 v3, 31, v2
	v_ashrrev_i32_e32 v2, 6, v2
	v_add_u32_e32 v50, v2, v3
	v_mul_i32_i24_e32 v9, 0x120, v50
	v_sub_u32_e32 v60, v80, v9
	v_add_u32_e32 v12, s35, v50
	v_mov_b64_e32 v[2:3], s[78:79]
	v_add_u32_e32 v4, 0x1200, v60
	v_mad_i64_i32 v[2:3], s[56:57], v12, s40, v[2:3]
	v_lshl_add_u64 v[2:3], v[4:5], 1, v[2:3]
	global_load_ushort v20, v[2:3], off
	v_add_co_u32_e32 v8, vcc, 0xffffd800, v2
	s_nop 1
	v_addc_co_u32_e32 v9, vcc, -1, v3, vcc
	global_load_ushort v30, v[8:9], off
	v_lshl_add_u64 v[8:9], v[4:5], 2, s[68:69]
	global_load_dword v40, v[8:9], off
	v_add_u32_e32 v81, 512, v138
	v_mul_hi_i32 v2, v81, s39
	v_lshrrev_b32_e32 v3, 31, v2
	v_ashrrev_i32_e32 v2, 6, v2
	v_add_u32_e32 v51, v2, v3
	v_mul_i32_i24_e32 v9, 0x120, v51
	v_sub_u32_e32 v61, v81, v9
	v_add_u32_e32 v12, s35, v51
	v_mov_b64_e32 v[2:3], s[78:79]
	v_add_u32_e32 v4, 0x1200, v61
	v_mad_i64_i32 v[2:3], s[56:57], v12, s40, v[2:3]
	v_lshl_add_u64 v[2:3], v[4:5], 1, v[2:3]
	global_load_ushort v21, v[2:3], off
	v_add_co_u32_e32 v8, vcc, 0xffffd800, v2
	s_nop 1
	v_addc_co_u32_e32 v9, vcc, -1, v3, vcc
	global_load_ushort v31, v[8:9], off
	v_lshl_add_u64 v[8:9], v[4:5], 2, s[68:69]
	global_load_dword v41, v[8:9], off
	v_add_u32_e32 v82, 1024, v138
	v_mul_hi_i32 v2, v82, s39
	v_lshrrev_b32_e32 v3, 31, v2
	v_ashrrev_i32_e32 v2, 6, v2
	v_add_u32_e32 v52, v2, v3
	v_mul_i32_i24_e32 v9, 0x120, v52
	v_sub_u32_e32 v62, v82, v9
	v_add_u32_e32 v12, s35, v52
	v_mov_b64_e32 v[2:3], s[78:79]
	v_add_u32_e32 v4, 0x1200, v62
	v_mad_i64_i32 v[2:3], s[56:57], v12, s40, v[2:3]
	v_lshl_add_u64 v[2:3], v[4:5], 1, v[2:3]
	global_load_ushort v22, v[2:3], off
	v_add_co_u32_e32 v8, vcc, 0xffffd800, v2
	s_nop 1
	v_addc_co_u32_e32 v9, vcc, -1, v3, vcc
	global_load_ushort v32, v[8:9], off
	v_lshl_add_u64 v[8:9], v[4:5], 2, s[68:69]
	global_load_dword v42, v[8:9], off
	v_add_u32_e32 v83, 1536, v138
	v_mul_hi_i32 v2, v83, s39
	v_lshrrev_b32_e32 v3, 31, v2
	v_ashrrev_i32_e32 v2, 6, v2
	v_add_u32_e32 v53, v2, v3
	v_mul_i32_i24_e32 v9, 0x120, v53
	v_sub_u32_e32 v63, v83, v9
	v_add_u32_e32 v12, s35, v53
	v_mov_b64_e32 v[2:3], s[78:79]
	v_add_u32_e32 v4, 0x1200, v63
	v_mad_i64_i32 v[2:3], s[56:57], v12, s40, v[2:3]
	v_lshl_add_u64 v[2:3], v[4:5], 1, v[2:3]
	global_load_ushort v23, v[2:3], off
	v_add_co_u32_e32 v8, vcc, 0xffffd800, v2
	s_nop 1
	v_addc_co_u32_e32 v9, vcc, -1, v3, vcc
	global_load_ushort v33, v[8:9], off
	v_lshl_add_u64 v[8:9], v[4:5], 2, s[68:69]
	global_load_dword v43, v[8:9], off
	v_add_u32_e32 v84, 2048, v138
	v_mul_hi_i32 v2, v84, s39
	v_lshrrev_b32_e32 v3, 31, v2
	v_ashrrev_i32_e32 v2, 6, v2
	v_add_u32_e32 v54, v2, v3
	v_mul_i32_i24_e32 v9, 0x120, v54
	v_sub_u32_e32 v64, v84, v9
	v_add_u32_e32 v12, s35, v54
	v_mov_b64_e32 v[2:3], s[78:79]
	v_add_u32_e32 v4, 0x1200, v64
	v_mad_i64_i32 v[2:3], s[56:57], v12, s40, v[2:3]
	v_lshl_add_u64 v[2:3], v[4:5], 1, v[2:3]
	global_load_ushort v24, v[2:3], off
	v_add_co_u32_e32 v8, vcc, 0xffffd800, v2
	s_nop 1
	v_addc_co_u32_e32 v9, vcc, -1, v3, vcc
	global_load_ushort v34, v[8:9], off
	v_lshl_add_u64 v[8:9], v[4:5], 2, s[68:69]
	global_load_dword v44, v[8:9], off
	v_add_u32_e32 v85, 2560, v138
	v_mul_hi_i32 v2, v85, s39
	v_lshrrev_b32_e32 v3, 31, v2
	v_ashrrev_i32_e32 v2, 6, v2
	v_add_u32_e32 v55, v2, v3
	v_mul_i32_i24_e32 v9, 0x120, v55
	v_sub_u32_e32 v65, v85, v9
	v_add_u32_e32 v12, s35, v55
	v_mov_b64_e32 v[2:3], s[78:79]
	v_add_u32_e32 v4, 0x1200, v65
	v_mad_i64_i32 v[2:3], s[56:57], v12, s40, v[2:3]
	v_lshl_add_u64 v[2:3], v[4:5], 1, v[2:3]
	global_load_ushort v25, v[2:3], off
	v_add_co_u32_e32 v8, vcc, 0xffffd800, v2
	s_nop 1
	v_addc_co_u32_e32 v9, vcc, -1, v3, vcc
	global_load_ushort v35, v[8:9], off
	v_lshl_add_u64 v[8:9], v[4:5], 2, s[68:69]
	global_load_dword v45, v[8:9], off
	v_add_u32_e32 v86, 3072, v138
	v_mul_hi_i32 v2, v86, s39
	v_lshrrev_b32_e32 v3, 31, v2
	v_ashrrev_i32_e32 v2, 6, v2
	v_add_u32_e32 v56, v2, v3
	v_mul_i32_i24_e32 v9, 0x120, v56
	v_sub_u32_e32 v66, v86, v9
	v_add_u32_e32 v12, s35, v56
	v_mov_b64_e32 v[2:3], s[78:79]
	v_add_u32_e32 v4, 0x1200, v66
	v_mad_i64_i32 v[2:3], s[56:57], v12, s40, v[2:3]
	v_lshl_add_u64 v[2:3], v[4:5], 1, v[2:3]
	global_load_ushort v26, v[2:3], off
	v_add_co_u32_e32 v8, vcc, 0xffffd800, v2
	s_nop 1
	v_addc_co_u32_e32 v9, vcc, -1, v3, vcc
	global_load_ushort v36, v[8:9], off
	v_lshl_add_u64 v[8:9], v[4:5], 2, s[68:69]
	global_load_dword v46, v[8:9], off
	v_add_u32_e32 v87, 3584, v138
	v_mul_hi_i32 v2, v87, s39
	v_lshrrev_b32_e32 v3, 31, v2
	v_ashrrev_i32_e32 v2, 6, v2
	v_add_u32_e32 v57, v2, v3
	v_mul_i32_i24_e32 v9, 0x120, v57
	v_sub_u32_e32 v67, v87, v9
	v_add_u32_e32 v12, s35, v57
	v_mov_b64_e32 v[2:3], s[78:79]
	v_add_u32_e32 v4, 0x1200, v67
	v_mad_i64_i32 v[2:3], s[56:57], v12, s40, v[2:3]
	v_lshl_add_u64 v[2:3], v[4:5], 1, v[2:3]
	global_load_ushort v27, v[2:3], off
	v_add_co_u32_e32 v8, vcc, 0xffffd800, v2
	s_nop 1
	v_addc_co_u32_e32 v9, vcc, -1, v3, vcc
	global_load_ushort v37, v[8:9], off
	v_lshl_add_u64 v[8:9], v[4:5], 2, s[68:69]
	global_load_dword v47, v[8:9], off
	v_add_u32_e32 v88, 4096, v138
	v_mul_hi_i32 v2, v88, s39
	v_lshrrev_b32_e32 v3, 31, v2
	v_ashrrev_i32_e32 v2, 6, v2
	v_add_u32_e32 v58, v2, v3
	v_mul_i32_i24_e32 v9, 0x120, v58
	v_sub_u32_e32 v68, v88, v9
	v_add_u32_e32 v12, s35, v58
	v_mov_b64_e32 v[2:3], s[78:79]
	v_add_u32_e32 v4, 0x1200, v68
	v_mad_i64_i32 v[2:3], s[56:57], v12, s40, v[2:3]
	v_lshl_add_u64 v[2:3], v[4:5], 1, v[2:3]
	global_load_ushort v28, v[2:3], off
	v_add_co_u32_e32 v8, vcc, 0xffffd800, v2
	s_nop 1
	v_addc_co_u32_e32 v9, vcc, -1, v3, vcc
	global_load_ushort v38, v[8:9], off
	v_lshl_add_u64 v[8:9], v[4:5], 2, s[68:69]
	global_load_dword v48, v[8:9], off
	s_cmp_lg_u32 s9, 0
	s_cbranch_scc1 .Lb1s_nosp_ld
	v_readlane_b32 s20, v255, 41
	v_readlane_b32 s21, v255, 42
	s_cmp_eq_u64 s[20:21], 0
	s_cbranch_scc1 .Lb1s_nosp_ld
	v_cmp_eq_u32_e32 vcc, 0, v50
	s_and_saveexec_b64 s[16:17], vcc
	v_add_u32_e32 v4, 0x1200, v60
	v_lshl_add_u64 v[2:3], v[4:5], 1, s[14:15]
	global_load_ushort v70, v[2:3], off
	s_mov_b64 exec, s[16:17]
